# dif attention: wave-skew sleep and its branch removed from the tile loop (skew was purely additive)
# speedup vs baseline: 1.0017x; 1.0017x over previous
; #define LAS __attribute__((address_space(3)))
; __device__ __forceinline__ float shx(float v, int mask, int lane) { return __int_as_float(__builtin_amdgcn_ds_bpermute((lane ^ mask) << 2, __float_as_int(v))); }
; __device__ __forceinline__ void attn_dif_unit(LAS unsigned char* lds, const int tid, const int wave_s, const bf16_t* q, const bf16_t* k0, const bf16_t* k1, const bf16_t* vt0, const bf16_t* vt1, ...
;     ...
;         asm volatile("s_waitcnt lgkmcnt(0)" ::: "memory"); __builtin_amdgcn_s_barrier(); asm volatile("" ::: "memory");
;         if (wave_s >= 4) __builtin_amdgcn_s_sleep(DA_SKEW);
; #pragma unroll
;         for (int m = 0; m < 2; ++m) {
;             f32x16 sacc[2]; const float nm = -m_used[m];
;             {
;                 bf16x8 qf[4], kfa[4], kfb[4];
; #pragma unroll
;                 for (int ks = 0; ks < 4; ++ks) qf[ks] = *(const LAS bf16x8*)(qb + c32 * DA_KP + m * 128 + ks * 32 + hi * 16);
; #pragma unroll
;                 for (int ks = 0; ks < 4; ++ks) kfa[ks] = *(const LAS bf16x8*)(kb + c32 * DA_KP + m * 128 + ks * 32 + hi * 16);
; #pragma unroll
;                 for (int ks = 0; ks < 4; ++ks) kfb[ks] = *(const LAS bf16x8*)(kb + (32 + c32) * DA_KP + m * 128 + ks * 32 + hi * 16);
; #pragma unroll
;                 for (int r = 0; r < 16; ++r) { sacc[0][r] = nm; sacc[1][r] = nm; }
; #pragma unroll
;                 for (int ks = 0; ks < 4; ++ks) sacc[0] = __builtin_amdgcn_mfma_f32_32x32x16_bf16(kfa[ks], qf[ks], sacc[0], 0, 0, 0);
; #pragma unroll
;                 for (int ks = 0; ks < 4; ++ks) sacc[1] = __builtin_amdgcn_mfma_f32_32x32x16_bf16(kfb[ks], qf[ks], sacc[1], 0, 0, 0);
;             }
;             float mx = fmaxf(sacc[0][0], sacc[1][0]);
; #pragma unroll
;             for (int a = 0; a < 2; ++a)
; #pragma unroll
;                 for (int r = 1; r < 16; r += 2) mx = fmaxf(fmaxf(mx, sacc[a][r]), sacc[a][r + 1 < 16 ? r + 1 : r]);
;             mx = fmaxf(mx, shx(mx, 32, lane));
.Ldif_noload:
.LBB0_989:
	v_mul_u32_u24_e32 v0, 0x110, v208
	v_add_u32_e32 v0, s22, v0
	v_add_u32_e32 v252, v0, v213
	ds_read_b128 v[2:5], v215
	ds_read_b128 v[6:9], v252
	v_xor_b32_e32 v144, 0x80000000, v218
	v_mov_b32_e32 v145, v144
	v_mov_b32_e32 v146, v144
	v_mov_b32_e32 v147, v144
	v_mov_b32_e32 v148, v144
	v_mov_b32_e32 v149, v144
	v_mov_b32_e32 v150, v144
	v_mov_b32_e32 v151, v144
	v_mov_b32_e32 v152, v144
	v_mov_b32_e32 v153, v144
	v_mov_b32_e32 v154, v144
	v_mov_b32_e32 v155, v144
	v_mov_b32_e32 v156, v144
	v_mov_b32_e32 v157, v144
	v_mov_b32_e32 v158, v144
	v_mov_b32_e32 v159, v144
	s_cmp_eq_u32 s55, 1
	s_cselect_b64 s[6:7], -1, 0
	s_waitcnt lgkmcnt(0)
	v_mfma_f32_32x32x16_bf16 v[160:175], v[6:9], v[2:5], v[144:159]
	ds_read_b128 v[6:9], v252 offset:32
	ds_read_b128 v[10:13], v215 offset:32
	s_cmp_lg_u32 s55, 1
	s_cselect_b64 s[10:11], -1, 0
	s_and_b64 vcc, exec, s[10:11]
	s_waitcnt lgkmcnt(0)
	v_mfma_f32_32x32x16_bf16 v[160:175], v[6:9], v[10:13], v[160:175]
	ds_read_b128 v[6:9], v252 offset:64
	ds_read_b128 v[192:195], v215 offset:64
	s_waitcnt lgkmcnt(0)
	v_mfma_f32_32x32x16_bf16 v[160:175], v[6:9], v[192:195], v[160:175]
	ds_read_b128 v[6:9], v252 offset:8704
	s_waitcnt lgkmcnt(0)
	v_mfma_f32_32x32x16_bf16 v[144:159], v[6:9], v[2:5], v[144:159]
	ds_read_b128 v[2:5], v252 offset:8736
	s_waitcnt lgkmcnt(0)
	v_mfma_f32_32x32x16_bf16 v[144:159], v[2:5], v[10:13], v[144:159]
	ds_read_b128 v[2:5], v252 offset:8768
	s_waitcnt lgkmcnt(0)
	v_mfma_f32_32x32x16_bf16 v[144:159], v[2:5], v[192:195], v[144:159]
	ds_read_b128 v[2:5], v252 offset:8800
	ds_read_b128 v[6:9], v215 offset:96
	s_waitcnt lgkmcnt(0)
	v_mfma_f32_32x32x16_bf16 v[144:159], v[2:5], v[6:9], v[144:159]
	ds_read_b128 v[2:5], v252 offset:96
	s_waitcnt lgkmcnt(0)
	v_mfma_f32_32x32x16_bf16 v[160:175], v[2:5], v[6:9], v[160:175]
	s_nop 8
	v_max_f32_e32 v0, v144, v144
	s_nop 1
	v_max_f32_e32 v2, v160, v160
	v_max_f32_e32 v0, v2, v0
	v_max3_f32 v0, v0, v161, v162
	v_max3_f32 v0, v0, v163, v164
	v_max3_f32 v0, v0, v165, v166
	v_max3_f32 v0, v0, v167, v168
	v_max3_f32 v0, v0, v169, v170
	v_max3_f32 v0, v0, v171, v172
	v_max3_f32 v0, v0, v173, v174
	v_max3_f32 v0, v0, v175, v145
	v_max3_f32 v0, v0, v146, v147
	v_max3_f32 v0, v0, v148, v149
	v_max3_f32 v0, v0, v150, v151
	v_max3_f32 v0, v0, v152, v153
	v_max3_f32 v0, v0, v154, v155
	v_max3_f32 v0, v0, v156, v157
	v_max3_f32 v0, v0, v158, v159
	ds_bpermute_b32 v2, v203, v0
	s_waitcnt lgkmcnt(0)
	v_max_f32_e32 v2, v2, v2
	v_max_f32_e32 v192, v0, v2
	s_cbranch_vccz .LBB0_993
	v_cmp_lt_f32_e32 vcc, s64, v192
	s_mov_b64 s[14:15], 0
	s_mov_b64 s[12:13], 0
	s_cbranch_vccz .LBB0_992
	v_max_f32_e32 v0, v192, v192
	v_max_f32_e32 v0, 0, v0
	s_mov_b64 s[12:13], -1
